# P4 A operand staged chunk-major in each LDS subtile: 16 adjacent LDS-DMA lanes fetch 256 contiguous bytes of one YA8 group; MFMA lane reads its own slot (original YA8 layout, P3 untouched)
# speedup vs baseline: 1.0101x; 1.0015x over previous
; #define PG8_WAIT_V(n) asm volatile("s_waitcnt vmcnt(" #n ")" ::: "memory")
; #define PG8_BAR __builtin_amdgcn_s_barrier()
; template <class Epi, class Sched>
; __device__ __forceinline__ void gemm_phase(PG8_LAS unsigned char* lds, const Gemm g, const Sched& S, const Epi& E, int wave_) {
;     const int wid = wave_, lane = lane_id_asm(), tid = wid * 64 + lane, wr = wid >> 2, wc = wid & 3, fr = lane & 15, fq = lane >> 4;
;     const int K = g.K, nt = K / BK;
;     unsigned voffA[2], voffB[2];
; #pragma unroll
;     for (int i = 0; i < 2; ++i) { int R, C; stage_rc(tid * 16 + i * 8192, R, C); const int Rb = Epi::PERM ? ((R & ~31) + perm32(R & 31)) : R;
;         voffA[i] = g.a_gm == 2 ? (unsigned)(((C >> 3) * SEQ + R) * 16) : g.a_gm ? (unsigned)(((C >> 4) * SEQ + R) * 32 + (C & 15) * 2) : (unsigned)(R * g.lda + C) * 2u; voffB[i] = (unsigned)(Rb * g.ldb + C) * 2u; }
;     const int gmb = g.a_gm == 2 ? 16 : 32;
;     const size_t kstep = (size_t)(BK * 2), kstepA = g.a_gm ? (size_t)(128 / gmb) * SEQ * gmb : kstep;
;     const size_t hsA = g.a_gm ? (size_t)HALF * gmb : (size_t)HALF * g.lda * 2, hsB = (size_t)HALF * g.ldb * 2;
;     ...
;     const unsigned ldsw = (unsigned)wid * 1024u;
;     const int aoff = lds_byte(wr * 64 + fr, fq * 8), boff = lds_byte(wc * 32 + fr, fq * 8);
;     ...
;     Unit cur, nxt; int ui = 0;
;     if (!S.next(0, cur)) return;
;     f32x4 acc[2][2][4][2];
; #pragma unroll
;     for (int a = 0; a < 2; ++a)
; #pragma unroll
;         for (int b = 0; b < 2; ++b)
; #pragma unroll
;             for (int m = 0; m < 4; ++m)
; #pragma unroll
;                 for (int n = 0; n < 2; ++n) acc[a][b][m][n] = (f32x4){0.f, 0.f, 0.f, 0.f};
;     i32x8 At[4], B0[2], B1[2];
;     const char* cA = PG8_PANEL_A(cur); const char* cB = (const char*)(g.Bt + (size_t)cur.grp * g.b_gs) + (size_t)cur.pn * 2 * hsB;
;     PG8_STAGE(PG8_SB(0, 0), cB, voffB); PG8_STAGE(PG8_SB(0, 1), cB + hsB, voffB); PG8_STAGE(PG8_SA(0, 0), cA, voffA); PG8_STAGE(PG8_SA(0, 1), cA + hsA, voffA);
;     if (wr == 1) PG8_BAR;
;     PG8_WAIT_V(2); PG8_BAR;
;     PG8_STAGE(PG8_SB(1, 0), cB + kstep, voffB); PG8_STAGE(PG8_SA(1, 0), cA + kstepA, voffA); PG8_STAGE(PG8_SB(1, 1), cB + hsB + kstep, voffB); PG8_STAGE(PG8_SA(1, 1), cA + kstepA + hsA, voffA);
; __global__ void __launch_bounds__(NWAVES * 64, 2) trunk_fwd(Args a) {
;     ...
;     if (IN(4)) REPEAT(4) { F.lane = lane_id_asm(); F.tid = F.wave * 64 + F.lane;
.LBB0_477:
	s_cmp_lt_i32 s14, 5
	s_cselect_b64 s[4:5], -1, 0
	s_and_b64 s[0:1], s[4:5], s[0:1]
	s_andn2_b64 vcc, exec, s[0:1]
	s_cbranch_vccnz .LBB0_506
	s_cmpk_gt_i32 s2, 0x7ff
	v_mbcnt_lo_u32_b32 v0, -1, 0
	v_mbcnt_hi_u32_b32 v0, -1, v0
	v_mbcnt_lo_u32_b32 v4, -1, 0
	v_mbcnt_hi_u32_b32 v4, -1, v4
	s_cbranch_scc1 .LBB0_506
	s_add_u32 s6, s30, 0x70400000
	s_addc_u32 s7, s31, 0
	s_add_u32 s33, s30, 0x11800000
	v_readlane_b32 s4, v252, 0
	s_addc_u32 s34, s31, 0
	s_lshr_b32 s18, s4, 8
	s_ashr_i32 s4, s2, 8
	s_lshr_b32 s5, s2, 31
	s_add_i32 s5, s4, s5
	s_and_b32 s9, s5, -2
	s_ashr_i32 s8, s5, 1
	s_sub_i32 s4, s4, s9
	s_lshl_b32 s10, s95, 10
	s_and_b32 s9, s8, 1
	s_sub_i32 s11, 1, s4
	s_cmp_eq_u32 s9, 0
	s_cselect_b32 s4, s4, s11
	s_lshl_b32 s9, s2, 3
	v_lshl_add_u32 v0, v4, 4, s10
	s_and_b32 s9, s9, 8
	s_bfe_u32 s11, s2, 0x30003
	v_add_u32_e32 v1, 0x2000, v0
	s_lshl_b32 s8, s8, 4
	s_or_b32 s9, s9, s11
	v_ashrrev_i32_e32 v2, 31, v1
	s_or_b32 s86, s9, s8
	s_lshl_b32 s8, s2, 1
	v_lshrrev_b32_e32 v2, 22, v2
	s_lshl_b32 s4, s4, 4
	s_and_b32 s8, s8, 12
	v_add_u32_e32 v2, v1, v2
	s_or_b32 s4, s4, s8
	s_bfe_u32 s8, s2, 0x20006
	v_ashrrev_i32_e32 v2, 10, v2
	s_waitcnt lgkmcnt(0)
	s_or_b32 s52, s4, s8
	s_ashr_i32 s4, s5, 2
	v_mul_i32_i24_e32 v3, 0x400, v2
	s_ashr_i32 s5, s4, 31
	v_sub_u32_e32 v1, v1, v3
	s_lshl_b32 s8, s86, 12
	s_lshl_b64 s[4:5], s[4:5], 26
	v_lshrrev_b32_e32 v3, 4, v1
	s_add_u32 s9, s6, s4
	v_bitop3_b32 v1, v3, v1, 32 bitop3:0x6c
	s_addc_u32 s11, s7, s5
	s_ashr_i32 s53, s52, 31
	v_ashrrev_i32_e32 v3, 31, v1
	s_lshl_b64 s[4:5], s[52:53], 21
	v_lshrrev_b32_e32 v3, 26, v3
	s_add_u32 s56, s33, s4
	v_add_u32_e32 v3, v1, v3
	s_addc_u32 s57, s34, s5
	s_and_b32 s4, s8, 0x1f000
	v_ashrrev_i32_e32 v5, 6, v3
	v_and_b32_e32 v3, 0xffc0, v3
	s_add_u32 s54, s9, s4
	v_sub_u32_e32 v1, v1, v3
	s_addc_u32 s55, s11, 0
	v_lshlrev_b32_e32 v6, 3, v2
	v_lshrrev_b16_e32 v3, 7, v1
	s_cmp_eq_u32 s18, 1
	v_and_b32_e32 v6, -16, v6
	v_and_b32_e32 v3, 1, v3
	s_cselect_b64 s[4:5], -1, 0
	s_add_u32 s8, s56, 0x100000
	v_add_u32_e32 v8, v5, v6
	v_lshlrev_b32_e32 v2, 5, v2
	v_add_u16_e32 v1, v1, v3
	v_mov_b32_e32 v3, 1
	s_addc_u32 s9, s57, 0
	s_add_i32 s35, s10, 0
	v_and_b32_e32 v7, 3, v5
	s_mov_b32 s10, 0x7ffe0
	v_lshrrev_b32_e32 v9, 2, v8
	v_lshlrev_b32_e32 v10, 1, v8
	v_and_b32_e32 v2, 32, v2
	v_ashrrev_i16_sdwa v1, v3, sext(v1) dst_sel:DWORD dst_unused:UNUSED_PAD src0_sel:DWORD src1_sel:BYTE_0
	v_and_or_b32 v7, v8, s10, v7
	v_and_b32_e32 v9, 4, v9
	v_and_b32_e32 v10, 24, v10
	v_add_u32_sdwa v1, v2, sext(v1) dst_sel:DWORD dst_unused:UNUSED_PAD src0_sel:DWORD src1_sel:WORD_0
	v_or3_b32 v7, v7, v9, v10
	v_lshlrev_b32_e32 v2, 1, v1
	v_lshlrev_b32_e32 v1, 10, v1
	v_lshl_add_u32 v192, v7, 13, v2
	v_and_b32_e32 v7, 0xffffe000, v1
	v_ashrrev_i32_e32 v1, 31, v0
	v_lshrrev_b32_e32 v1, 22, v1
	v_add_u32_e32 v1, v0, v1
	v_ashrrev_i32_e32 v1, 10, v1
	v_mul_i32_i24_e32 v2, 0x400, v1
	v_sub_u32_e32 v0, v0, v2
	v_lshrrev_b32_e32 v2, 4, v0
	v_bitop3_b32 v0, v2, v0, 32 bitop3:0x6c
	v_ashrrev_i32_e32 v2, 31, v0
	v_lshrrev_b32_e32 v2, 26, v2
	v_add_u32_e32 v2, v0, v2
	v_lshlrev_b32_e32 v9, 3, v1
	v_add_lshl_u32 v194, v7, v8, 4
	v_ashrrev_i32_e32 v8, 6, v2
	v_and_b32_e32 v9, -16, v9
	v_and_b32_e32 v2, 0xc0, v2
	v_add_u32_e32 v11, v8, v9
	v_lshlrev_b32_e32 v1, 5, v1
	v_sub_u32_e32 v0, v0, v2
	v_and_b32_e32 v10, 3, v8
	v_lshrrev_b32_e32 v12, 2, v11
	v_lshlrev_b32_e32 v13, 1, v11
	v_and_b32_e32 v1, 32, v1
	v_ashrrev_i16_sdwa v0, v3, sext(v0) dst_sel:DWORD dst_unused:UNUSED_PAD src0_sel:DWORD src1_sel:BYTE_0
	v_and_or_b32 v10, v11, s10, v10
	v_and_b32_e32 v12, 4, v12
	v_and_b32_e32 v13, 24, v13
	v_add_u32_sdwa v0, v1, sext(v0) dst_sel:DWORD dst_unused:UNUSED_PAD src0_sel:DWORD src1_sel:WORD_0
	s_add_i32 s53, s35, 0x10000
	v_or3_b32 v10, v10, v12, v13
	v_lshlrev_b32_e32 v1, 1, v0
	s_add_i32 s66, s35, 0x12000
	v_lshl_add_u32 v196, v10, 13, v1
	s_mov_b32 m0, s53
	s_add_i32 s67, s35, 0x14000
	global_load_lds_dwordx4 v196, s[56:57]
	s_mov_b32 m0, s66
	s_add_i32 s68, s35, 0x16000
	v_lshlrev_b32_e32 v0, 10, v0
	global_load_lds_dwordx4 v192, s[56:57]
	s_mov_b32 m0, s67
	v_and_b32_e32 v10, 0xffffe000, v0
	v_mov_b32_e32 v201, 0
	global_load_lds_dwordx4 v196, s[8:9]
	s_mov_b32 m0, s68
	s_add_i32 s69, s35, 0x2000
	s_and_b32 s98, s95, 1
	s_lshl_b32 s98, s98, 19
	s_lshr_b32 s99, s95, 1
	s_lshl_b32 s99, s99, 8
	s_or_b32 s98, s98, s99
	v_and_b32_e32 v10, 48, v4
	v_lshlrev_b32_e32 v10, 13, v10
	v_and_b32_e32 v11, 15, v4
	v_lshl_or_b32 v10, v11, 4, v10
	v_or_b32_e32 v198, s98, v10
	v_add_u32_e32 v194, 0x400, v198
	v_lshlrev_b32_e32 v238, 4, v4
	global_load_lds_dwordx4 v192, s[8:9]
	v_mov_b32_e32 v199, v201
	s_mov_b32 m0, s35
	s_add_i32 s72, s35, 0x4000
	v_lshl_add_u64 v[0:1], s[54:55], 0, v[198:199]
	global_load_lds_dwordx4 v198, s[54:55]
	v_mov_b32_e32 v195, v201
	s_mov_b32 m0, s69
	s_mov_b64 s[8:9], 0x800
	s_add_i32 s73, s35, 0x6000
	v_lshl_add_u64 v[2:3], s[54:55], 0, v[194:195]
	global_load_lds_dwordx4 v194, s[54:55]
	v_lshl_add_u64 v[0:1], v[0:1], 0, s[8:9]
	s_mov_b32 m0, s72
	v_mov_b32_e32 v197, v201
	global_load_lds_dwordx4 v[0:1], off
	v_lshl_add_u64 v[0:1], v[2:3], 0, s[8:9]
	s_mov_b32 m0, s73
	v_mov_b32_e32 v193, v201
	global_load_lds_dwordx4 v[0:1], off
	s_mov_b32 s74, 0
	s_cmp_lg_u32 s18, 1
	v_lshl_add_u64 v[2:3], s[56:57], 0, v[196:197]
	v_lshl_add_u64 v[0:1], s[56:57], 0, v[192:193]
	s_cbranch_scc1 .LBB0_481
	s_barrier
;     __device__ __forceinline__ bool next(int i, Unit& u) const { const int L = i * G + c; if (L >= nM * nN) return false; static_unit(L, nM, nN, u.pm, u.pn); u.grp = 0; return true; }
;     __device__ __forceinline__ bool next(int i, Unit& u) const { const int L = i * G + c; if (L >= 256) return false; const int cu = L >> 2; u.grp = L & 3; u.pm = 64 + (cu >> 5); u.pn = cu & 31; return true; }
;     __device__ __forceinline__ bool next(int i, Unit& u) const { const int L = i * G + c; if (L >= 2048) return false; u.grp = L >> 9; static_unit(L & 511, 64, 8, u.pm, u.pn); return true; }
; template <class Epi, class Sched>
; __device__ __forceinline__ void gemm_phase(PG8_LAS unsigned char* lds, const Gemm g, const Sched& S, const Epi& E, int wave_) {
;     ...
;         voffA[i] = g.a_gm == 2 ? (unsigned)(((C >> 3) * SEQ + R) * 16) : g.a_gm ? (unsigned)(((C >> 4) * SEQ + R) * 32 + (C & 15) * 2) : (unsigned)(R * g.lda + C) * 2u; voffB[i] = (unsigned)(Rb * g.ldb + C) * 2u; }
;     const int gmb = g.a_gm == 2 ? 16 : 32;
;     const size_t kstep = (size_t)(BK * 2), kstepA = g.a_gm ? (size_t)(128 / gmb) * SEQ * gmb : kstep;
;     const size_t hsA = g.a_gm ? (size_t)HALF * gmb : (size_t)HALF * g.lda * 2, hsB = (size_t)HALF * g.ldb * 2;
;     ...
;     const unsigned ldsw = (unsigned)wid * 1024u;
;     const int aoff = lds_byte(wr * 64 + fr, fq * 8), boff = lds_byte(wc * 32 + fr, fq * 8);
;     ...
;     Unit cur, nxt; int ui = 0;
;     if (!S.next(0, cur)) return;
;     f32x4 acc[2][2][4][2];
; #pragma unroll
;     for (int a = 0; a < 2; ++a)
; #pragma unroll
;         for (int b = 0; b < 2; ++b)
; #pragma unroll
;             for (int m = 0; m < 4; ++m)
; #pragma unroll
;                 for (int n = 0; n < 2; ++n) acc[a][b][m][n] = (f32x4){0.f, 0.f, 0.f, 0.f};
;     i32x8 At[4], B0[2], B1[2];
;     const char* cA = PG8_PANEL_A(cur); const char* cB = (const char*)(g.Bt + (size_t)cur.grp * g.b_gs) + (size_t)cur.pn * 2 * hsB;
;     PG8_STAGE(PG8_SB(0, 0), cB, voffB); PG8_STAGE(PG8_SB(0, 1), cB + hsB, voffB); PG8_STAGE(PG8_SA(0, 0), cA, voffA); PG8_STAGE(PG8_SA(0, 1), cA + hsA, voffA);
;     if (wr == 1) PG8_BAR;
;     PG8_WAIT_V(2); PG8_BAR;
;     PG8_STAGE(PG8_SB(1, 0), cB + kstep, voffB); PG8_STAGE(PG8_SA(1, 0), cA + kstepA, voffA); PG8_STAGE(PG8_SB(1, 1), cB + hsB + kstep, voffB); PG8_STAGE(PG8_SA(1, 1), cA + kstepA + hsA, voffA);
;     PG8_WAIT_V(0); PG8_BAR;
.LBB0_481:
	s_add_u32 s10, s30, 0x4c400000
	s_addc_u32 s11, s31, 0
	s_add_u32 s12, s30, 0x3c400000
	s_addc_u32 s13, s31, 0
	s_add_u32 s16, s30, 0x2bc00000
	s_addc_u32 s17, s31, 0
	s_lshl_b32 s75, s18, 6
	s_lshl_b32 s50, s18, 13
	s_lshl_b32 s18, s95, 5
	s_and_b32 s51, s18, 0x60
	s_lshr_b32 s58, s51, 3
	s_add_u32 s40, s54, 0x100000
	s_addc_u32 s41, s55, 0
	s_add_u32 s42, s56, 0x100080
	s_addc_u32 s43, s57, 0
	s_add_u32 s46, s54, 0x100800
	s_addc_u32 s47, s55, 0
	v_readlane_b32 s18, v252, 0
	s_cmpk_lt_u32 s18, 0x100
	s_cselect_b64 s[18:19], -1, 0
	s_add_u32 s22, s30, 0x1780004
	s_addc_u32 s23, s31, 0
	s_mov_b64 s[38:39], 0x80
	s_add_i32 s76, s35, 0x18000
	v_lshl_add_u64 v[2:3], v[2:3], 0, s[38:39]
	s_mov_b32 m0, s76
	s_add_i32 s77, s35, 0x1a000
	s_waitcnt vmcnt(2)
	s_barrier
	global_load_lds_dwordx4 v[2:3], off
	v_lshl_add_u64 v[0:1], v[0:1], 0, s[38:39]
	s_mov_b32 m0, s77
	s_add_i32 s78, s35, 0x8000
	global_load_lds_dwordx4 v[0:1], off
	v_lshl_add_u64 v[0:1], s[40:41], 0, v[198:199]
	s_mov_b32 m0, s78
	s_add_i32 s79, s35, 0xa000
	global_load_lds_dwordx4 v[0:1], off
	v_lshl_add_u64 v[0:1], s[40:41], 0, v[194:195]
	s_mov_b32 m0, s79
	s_add_i32 s80, s35, 0x1c000
	global_load_lds_dwordx4 v[0:1], off
	v_lshl_add_u64 v[0:1], s[42:43], 0, v[196:197]
	s_mov_b32 m0, s80
	s_add_i32 s81, s35, 0x1e000
	global_load_lds_dwordx4 v[0:1], off
	v_lshl_add_u64 v[0:1], s[42:43], 0, v[192:193]
	s_mov_b32 m0, s81
	s_add_i32 s82, s35, 0xc000
	global_load_lds_dwordx4 v[0:1], off
	v_lshl_add_u64 v[0:1], s[46:47], 0, v[198:199]
	s_mov_b32 m0, s82
	s_add_i32 s83, s35, 0xe000
	global_load_lds_dwordx4 v[0:1], off
	v_lshl_add_u64 v[0:1], s[46:47], 0, v[194:195]
	s_mov_b32 m0, s83
	v_and_b32_e32 v220, 15, v4
	global_load_lds_dwordx4 v[0:1], off
	v_ashrrev_i32_e32 v0, 1, v4
	v_and_b32_e32 v1, -8, v0
	v_ashrrev_i32_e32 v2, 6, v4
	v_and_b32_e32 v3, 48, v4
	v_lshlrev_b32_e32 v4, 2, v4
	v_lshl_or_b32 v3, v220, 6, v3
	v_and_b32_e32 v4, 32, v4
	v_add_u32_e32 v225, s51, v1
	v_add_u32_e32 v1, v8, v10
	s_mov_b64 s[40:41], 0x100800
	v_add_u32_e32 v11, s58, v2
	s_waitcnt vmcnt(0)
	v_xad_u32 v3, v3, v4, 0
	v_mov_b32_e32 v200, v198
	v_add_u32_e32 v1, v5, v7
	v_lshl_add_u32 v4, v11, 10, v3
	v_lshl_add_u32 v2, v2, 10, v3
	v_and_b32_e32 v0, 8, v0
	v_lshl_add_u64 v[202:203], v[200:201], 0, s[40:41]
	v_mov_b32_e32 v200, v194
	v_add_u32_e32 v221, 0x10000, v4
	v_add_u32_e32 v222, 0x14000, v4
	v_add_u32_e32 v223, 0x18000, v4
	v_add_u32_e32 v224, 0x1c000, v4
	v_add_u32_e32 v226, 0x10400, v4
	v_add_u32_e32 v227, 0x10800, v4
	v_add_u32_e32 v228, 0x10c00, v4
	v_add_u32_e32 v229, 0x14400, v4
	v_add_u32_e32 v230, 0x14800, v4
	v_add_u32_e32 v231, 0x14c00, v4
	v_add_u32_e32 v232, 0x18400, v4
	v_add_u32_e32 v233, 0x18800, v4
	v_add_u32_e32 v234, 0x18c00, v4
	v_add_u32_e32 v235, 0x1c400, v4
	v_add_u32_e32 v236, 0x1c800, v4
	v_add_u32_e32 v237, 0x1cc00, v4
	v_lshl_add_u64 v[204:205], v[200:201], 0, s[40:41]
	v_add_u32_e32 v238, s50, v238
	v_lshlrev_b32_e32 v206, 1, v0
	s_mov_b32 s84, 0x200000
	s_barrier
	s_branch .LBB0_484
